# cvhost: all hosted work in barrier-arrival windows (consume+stores before barrier A, next loads before barrier B, each after a full drain and followed by a counted wait)
# baseline (speedup 1.0000x reference)
.Lcv_s2done:
.Lcv_prepdone:
	v_lshl_add_u64 v[112:113], s[28:29], 0, v[146:147]
	s_mov_b64 s[54:55], 0x18fc0000
	s_mov_b32 m0, s78
	v_lshl_add_u64 v[100:101], v[112:113], 0, s[54:55]
	s_add_i32 s98, s87, -1
	s_cmp_gt_u32 s98, 19
	s_cbranch_scc1 .Lcv_wa0
	s_waitcnt vmcnt(2)
	s_branch .Lcv_wad

; template <int NB>
; __device__ __forceinline__ void p0_batch(int it0, int stride, int lane, const P0Ptrs& a) {
;     ...
;     for (int q = 0; q < NB; ++q) { const bool ok = it0 < NFAST / 4; d[q] = p0_desc(p0_super(ok ? it0 : 0, q), lane, a); if (!ok) d[q].dst = nullptr;
; #pragma unroll
;         for (int i = 0; i < 8; ++i) v[q][i] = __builtin_nontemporal_load((const f32x4*)(d[q].src + (size_t)i * d[q].nsrc));
;         const float* kp = d[q].ks ? d[q].ks : a.ffn_g;
;         s0[q] = *(const f32x4*)(kp); s1[q] = *(const f32x4*)(kp + 4); }
.LBB0_764:
	s_cmp_gt_u32 s87, 20
	s_cbranch_scc1 .Lcv_done
	s_cmp_gt_u32 s87, 19
	s_cbranch_scc1 .Lcv_inc
	s_waitcnt vmcnt(0)
	v_and_b32_e32 v207, 63, v0
	v_lshrrev_b32_e32 v208, 2, v207
	v_and_b32_e32 v209, 3, v207
	v_lshlrev_b32_e32 v209, 4, v209
	v_mad_u32_u24 v210, v208, s90, v209
	v_lshlrev_b32_e32 v211, 2, v208
	s_lshl_b32 s98, s90, 4
	global_load_dwordx4 v[238:241], v210, s[88:89] nt
	global_load_dwordx4 v[242:245], v210, s[88:89] offset:64 nt
	global_load_dword v237, v211, s[94:95]
	s_add_u32 s88, s88, s98
	s_addc_u32 s89, s89, 0
	s_add_u32 s94, s94, 64
	s_addc_u32 s95, s95, 0
	s_and_b32 s98, s87, 3
	s_cmp_lg_u32 s98, 3
	s_cbranch_scc1 .Lcv_inc
	s_cmp_gt_u32 s87, 18
	s_cbranch_scc1 .Lcv_inc
	s_add_i32 s99, s32, 1
	s_movk_i32 s98, 0x78
	s_cmp_lt_u32 s99, 7
	s_cselect_b32 s98, 0x60, s98
	s_cmp_eq_u32 s99, 0
	s_cselect_b32 s98, 0x50, s98
	s_cselect_b32 s99, 0, 0x58
	s_load_dwordx2 s[88:89], s[100:101], s98
	s_cmp_eq_u32 s99, 0
	s_cbranch_scc0 .Lcv_s1b_s
	s_bfe_u32 s99, s2, 0x50003
	s_cmp_lt_u32 s99, 16
	s_cselect_b32 s99, 64, 0x48
